# phase B sample-row split-K GEMM: 8 tasks of weight loads in flight instead of serialized per-task loads
# baseline (speedup 1.0000x reference)
; __device__ __forceinline__ int lane_fresh() { int l; asm volatile("v_mbcnt_lo_u32_b32 %0, -1, 0\n\tv_mbcnt_hi_u32_b32 %0, -1, %0" : "=v"(l)); return l; }
; #define MFMA16(a, b, c) __builtin_amdgcn_mfma_f32_16x16x32_bf16((a), (b), (c), 0, 0, 0)
; template <int NT, class FA, class FB, class FL>
; __device__ __forceinline__ void skgemm(FA aptr, FB bptr, FL ldf, const int KS, const int wv) {
;   float* part = (float*)g_shm;
;   const int lane = lane_fresh(), fr = lane & 15, fq = lane >> 4;
;   __syncthreads();
; #pragma unroll
;   for (int i = 0; i < NT; ++i) {
;     f32x4 acc = {0.f, 0.f, 0.f, 0.f};
;     const int ld = ldf(i);
;     const u16* ap = aptr(i) + (size_t)fr * ld + wv * KS + fq * 8;
;     const u16* bp = bptr(i) + (size_t)fr * ld + wv * KS + fq * 8;
; #pragma unroll 8
;     for (int k = 0; k < KS; k += 32) acc = MFMA16(*(const bf16x8*)(bp + k), *(const bf16x8*)(ap + k), acc);
;     *(f32x4*)(part + ((i * 8 + wv) * 64 + lane) * 4) = acc;
;   }
;   __syncthreads();
; }
; __device__ __forceinline__ void phaseB(const Params& p, const int wv, const int rep) {
;     ...
;   for (int gb = blockIdx.x; gb < 256; gb += gridDim.x) {
;     const int task0 = gb * 14, mt = task0 / 448, nt0 = task0 - mt * 448;
;     const u16* Ab = XN + (size_t)(TP + mt * 16) * 1024;
;     const u16* Bb = (const u16*)(ws + OFF_WIN) + (size_t)(nt0 * 16) * 1024;
;     skgemm<14>([&](int) { return Ab; }, [&](int i) { return Bb + (size_t)i * 16 * 1024; }, [&](int) { return 1024; }, 128, wv);
.LBB0_225:
	s_ashr_i32 s23, s43, 31
	s_lshr_b32 s23, s23, 27
	s_add_i32 s23, s43, s23
	s_ashr_i32 s26, s23, 5
	s_mul_i32 s22, s43, 14
	s_mul_i32 s23, s26, 0xfffffe40
	s_add_i32 s27, s23, s22
	s_lshl_b32 s22, s26, 4
	s_addk_i32 s22, 0x4000
	s_ashr_i32 s23, s22, 31
	s_lshl_b64 s[24:25], s[22:23], 11
	s_add_u32 s24, s48, s24
	s_addc_u32 s25, s49, s25
	s_lshl_b32 s28, s27, 4
	s_ashr_i32 s29, s28, 31
	v_mbcnt_lo_u32_b32 v56, -1, 0
	v_mbcnt_hi_u32_b32 v56, -1, v56
	s_lshl_b64 s[28:29], s[28:29], 11
	v_ashrrev_i32_e32 v0, 1, v56
	v_lshlrev_b32_e32 v2, 11, v56
	v_and_b32_e32 v0, -8, v0
	v_and_b32_e32 v52, 0x7800, v2
	s_add_u32 s28, s50, s28
	v_ashrrev_i32_e32 v1, 31, v0
	v_lshl_add_u64 v[2:3], s[24:25], 0, v[52:53]
	s_addc_u32 s29, s51, s29
	v_lshl_add_u64 v[2:3], v[2:3], 0, s[0:1]
	v_lshlrev_b64 v[0:1], 1, v[0:1]
	v_lshl_add_u64 v[86:87], v[2:3], 0, v[0:1]
	v_lshl_add_u64 v[2:3], s[28:29], 0, v[52:53]
	v_lshl_add_u64 v[2:3], v[2:3], 0, s[0:1]
	v_lshl_add_u64 v[54:55], v[2:3], 0, v[0:1]
	s_mov_b32 s23, 0x8000
	v_add_co_u32_e32 v8, vcc, s23, v54
	s_mov_b32 s23, 0x10000
	s_nop 0
	v_addc_co_u32_e32 v9, vcc, 0, v55, vcc
	s_waitcnt vmcnt(0) lgkmcnt(0)
	s_barrier
	v_and_b32_e32 v248, 15, v56
	v_lshlrev_b32_e32 v248, 11, v248
	v_lshrrev_b32_e32 v249, 4, v56
	v_lshl_add_u32 v248, v249, 4, v248
	v_add_u32_e32 v248, s0, v248
	v_lshlrev_b32_e32 v249, 4, v56
	v_add_u32_e32 v249, s13, v249
	v_add_u32_e32 v62, 0x10000, v249
	global_load_dwordx4 v[0:3], v248, s[24:25]
	global_load_dwordx4 v[4:7], v248, s[24:25] offset:64
	global_load_dwordx4 v[8:11], v248, s[24:25] offset:128
	global_load_dwordx4 v[12:15], v248, s[24:25] offset:192
	global_load_dwordx4 v[64:67], v248, s[28:29]
	global_load_dwordx4 v[68:71], v248, s[28:29] offset:64
	global_load_dwordx4 v[72:75], v248, s[28:29] offset:128
	global_load_dwordx4 v[76:79], v248, s[28:29] offset:192
	s_add_u32 s28, s28, 0x8000
	s_addc_u32 s29, s29, 0
	global_load_dwordx4 v[80:83], v248, s[28:29]
	global_load_dwordx4 v[84:87], v248, s[28:29] offset:64
	global_load_dwordx4 v[88:91], v248, s[28:29] offset:128
	global_load_dwordx4 v[92:95], v248, s[28:29] offset:192
	s_add_u32 s28, s28, 0x8000
	s_addc_u32 s29, s29, 0
	global_load_dwordx4 v[96:99], v248, s[28:29]
	global_load_dwordx4 v[100:103], v248, s[28:29] offset:64
	global_load_dwordx4 v[104:107], v248, s[28:29] offset:128
	global_load_dwordx4 v[108:111], v248, s[28:29] offset:192
	s_add_u32 s28, s28, 0x8000
	s_addc_u32 s29, s29, 0
	global_load_dwordx4 v[112:115], v248, s[28:29]
	global_load_dwordx4 v[116:119], v248, s[28:29] offset:64
	global_load_dwordx4 v[120:123], v248, s[28:29] offset:128
	global_load_dwordx4 v[124:127], v248, s[28:29] offset:192
	s_add_u32 s28, s28, 0x8000
	s_addc_u32 s29, s29, 0
	global_load_dwordx4 v[128:131], v248, s[28:29]
	global_load_dwordx4 v[132:135], v248, s[28:29] offset:64
	global_load_dwordx4 v[136:139], v248, s[28:29] offset:128
	global_load_dwordx4 v[140:143], v248, s[28:29] offset:192
	s_add_u32 s28, s28, 0x8000
	s_addc_u32 s29, s29, 0
	global_load_dwordx4 v[144:147], v248, s[28:29]
	global_load_dwordx4 v[148:151], v248, s[28:29] offset:64
	global_load_dwordx4 v[152:155], v248, s[28:29] offset:128
	global_load_dwordx4 v[156:159], v248, s[28:29] offset:192
	s_add_u32 s28, s28, 0x8000
	s_addc_u32 s29, s29, 0
	global_load_dwordx4 v[160:163], v248, s[28:29]
	global_load_dwordx4 v[164:167], v248, s[28:29] offset:64
	global_load_dwordx4 v[168:171], v248, s[28:29] offset:128
	global_load_dwordx4 v[172:175], v248, s[28:29] offset:192
	s_add_u32 s28, s28, 0x8000
	s_addc_u32 s29, s29, 0
	global_load_dwordx4 v[176:179], v248, s[28:29]
	global_load_dwordx4 v[180:183], v248, s[28:29] offset:64
	global_load_dwordx4 v[184:187], v248, s[28:29] offset:128
	global_load_dwordx4 v[188:191], v248, s[28:29] offset:192
	s_add_u32 s28, s28, 0x8000
	s_addc_u32 s29, s29, 0
	s_waitcnt vmcnt(31)
	v_mfma_f32_16x16x32_bf16 v[192:195], v[64:67], v[0:3], 0
	s_waitcnt vmcnt(30)
	v_mfma_f32_16x16x32_bf16 v[192:195], v[68:71], v[4:7], v[192:195]
	s_waitcnt vmcnt(29)
	v_mfma_f32_16x16x32_bf16 v[192:195], v[72:75], v[8:11], v[192:195]
	s_waitcnt vmcnt(28)
	v_mfma_f32_16x16x32_bf16 v[192:195], v[76:79], v[12:15], v[192:195]
	global_load_dwordx4 v[64:67], v248, s[28:29]
	global_load_dwordx4 v[68:71], v248, s[28:29] offset:64
	global_load_dwordx4 v[72:75], v248, s[28:29] offset:128
	global_load_dwordx4 v[76:79], v248, s[28:29] offset:192
	s_add_u32 s28, s28, 0x8000
	s_addc_u32 s29, s29, 0
	s_waitcnt vmcnt(31)
	v_mfma_f32_16x16x32_bf16 v[196:199], v[80:83], v[0:3], 0
	s_waitcnt vmcnt(30)
	v_mfma_f32_16x16x32_bf16 v[196:199], v[84:87], v[4:7], v[196:199]
	s_waitcnt vmcnt(29)
	v_mfma_f32_16x16x32_bf16 v[196:199], v[88:91], v[8:11], v[196:199]
	s_waitcnt vmcnt(28)
	v_mfma_f32_16x16x32_bf16 v[196:199], v[92:95], v[12:15], v[196:199]
	global_load_dwordx4 v[80:83], v248, s[28:29]
	global_load_dwordx4 v[84:87], v248, s[28:29] offset:64
	global_load_dwordx4 v[88:91], v248, s[28:29] offset:128
	global_load_dwordx4 v[92:95], v248, s[28:29] offset:192
	s_add_u32 s28, s28, 0x8000
	s_addc_u32 s29, s29, 0
	s_waitcnt vmcnt(31)
	v_mfma_f32_16x16x32_bf16 v[200:203], v[96:99], v[0:3], 0
	s_waitcnt vmcnt(30)
	v_mfma_f32_16x16x32_bf16 v[200:203], v[100:103], v[4:7], v[200:203]
	s_waitcnt vmcnt(29)
	v_mfma_f32_16x16x32_bf16 v[200:203], v[104:107], v[8:11], v[200:203]
	s_waitcnt vmcnt(28)
	v_mfma_f32_16x16x32_bf16 v[200:203], v[108:111], v[12:15], v[200:203]
	global_load_dwordx4 v[96:99], v248, s[28:29]
	global_load_dwordx4 v[100:103], v248, s[28:29] offset:64
	global_load_dwordx4 v[104:107], v248, s[28:29] offset:128
	global_load_dwordx4 v[108:111], v248, s[28:29] offset:192
	s_add_u32 s28, s28, 0x8000
	s_addc_u32 s29, s29, 0
	ds_write_b128 v249, v[192:195]
	s_waitcnt vmcnt(31)
; __device__ __forceinline__ int lane_fresh() { int l; asm volatile("v_mbcnt_lo_u32_b32 %0, -1, 0\n\tv_mbcnt_hi_u32_b32 %0, -1, %0" : "=v"(l)); return l; }
; #define MFMA16(a, b, c) __builtin_amdgcn_mfma_f32_16x16x32_bf16((a), (b), (c), 0, 0, 0)
; template <int NT, class FA, class FB, class FL>
; __device__ __forceinline__ void skgemm(FA aptr, FB bptr, FL ldf, const int KS, const int wv) {
;   float* part = (float*)g_shm;
;   const int lane = lane_fresh(), fr = lane & 15, fq = lane >> 4;
;   __syncthreads();
; #pragma unroll
;   for (int i = 0; i < NT; ++i) {
;     f32x4 acc = {0.f, 0.f, 0.f, 0.f};
;     const int ld = ldf(i);
;     const u16* ap = aptr(i) + (size_t)fr * ld + wv * KS + fq * 8;
;     const u16* bp = bptr(i) + (size_t)fr * ld + wv * KS + fq * 8;
; #pragma unroll 8
;     for (int k = 0; k < KS; k += 32) acc = MFMA16(*(const bf16x8*)(bp + k), *(const bf16x8*)(ap + k), acc);
;     *(f32x4*)(part + ((i * 8 + wv) * 64 + lane) * 4) = acc;
;   }
;   __syncthreads();
; }
	v_mfma_f32_16x16x32_bf16 v[204:207], v[112:115], v[0:3], 0
	s_waitcnt vmcnt(30)
	v_mfma_f32_16x16x32_bf16 v[204:207], v[116:119], v[4:7], v[204:207]
	s_waitcnt vmcnt(29)
	v_mfma_f32_16x16x32_bf16 v[204:207], v[120:123], v[8:11], v[204:207]
	s_waitcnt vmcnt(28)
	v_mfma_f32_16x16x32_bf16 v[204:207], v[124:127], v[12:15], v[204:207]
	global_load_dwordx4 v[112:115], v248, s[28:29]
	global_load_dwordx4 v[116:119], v248, s[28:29] offset:64
	global_load_dwordx4 v[120:123], v248, s[28:29] offset:128
	global_load_dwordx4 v[124:127], v248, s[28:29] offset:192
	s_add_u32 s28, s28, 0x8000
	s_addc_u32 s29, s29, 0
	ds_write_b128 v249, v[196:199] offset:8192
	s_waitcnt vmcnt(31)
	v_mfma_f32_16x16x32_bf16 v[208:211], v[128:131], v[0:3], 0
	s_waitcnt vmcnt(30)
	v_mfma_f32_16x16x32_bf16 v[208:211], v[132:135], v[4:7], v[208:211]
	s_waitcnt vmcnt(29)
	v_mfma_f32_16x16x32_bf16 v[208:211], v[136:139], v[8:11], v[208:211]
	s_waitcnt vmcnt(28)
	v_mfma_f32_16x16x32_bf16 v[208:211], v[140:143], v[12:15], v[208:211]
	global_load_dwordx4 v[128:131], v248, s[28:29]
	global_load_dwordx4 v[132:135], v248, s[28:29] offset:64
	global_load_dwordx4 v[136:139], v248, s[28:29] offset:128
	global_load_dwordx4 v[140:143], v248, s[28:29] offset:192
	s_add_u32 s28, s28, 0x8000
	s_addc_u32 s29, s29, 0
	ds_write_b128 v249, v[200:203] offset:16384
	s_waitcnt vmcnt(31)
	v_mfma_f32_16x16x32_bf16 v[212:215], v[144:147], v[0:3], 0
	s_waitcnt vmcnt(30)
	v_mfma_f32_16x16x32_bf16 v[212:215], v[148:151], v[4:7], v[212:215]
	s_waitcnt vmcnt(29)
	v_mfma_f32_16x16x32_bf16 v[212:215], v[152:155], v[8:11], v[212:215]
	s_waitcnt vmcnt(28)
	v_mfma_f32_16x16x32_bf16 v[212:215], v[156:159], v[12:15], v[212:215]
	global_load_dwordx4 v[144:147], v248, s[28:29]
	global_load_dwordx4 v[148:151], v248, s[28:29] offset:64
	global_load_dwordx4 v[152:155], v248, s[28:29] offset:128
	global_load_dwordx4 v[156:159], v248, s[28:29] offset:192
	s_add_u32 s28, s28, 0x8000
	s_addc_u32 s29, s29, 0
	ds_write_b128 v249, v[204:207] offset:24576
	s_waitcnt vmcnt(31)
	v_mfma_f32_16x16x32_bf16 v[216:219], v[160:163], v[0:3], 0
	s_waitcnt vmcnt(30)
	v_mfma_f32_16x16x32_bf16 v[216:219], v[164:167], v[4:7], v[216:219]
	s_waitcnt vmcnt(29)
	v_mfma_f32_16x16x32_bf16 v[216:219], v[168:171], v[8:11], v[216:219]
	s_waitcnt vmcnt(28)
	v_mfma_f32_16x16x32_bf16 v[216:219], v[172:175], v[12:15], v[216:219]
	ds_write_b128 v249, v[208:211] offset:32768
	s_waitcnt vmcnt(27)
	v_mfma_f32_16x16x32_bf16 v[220:223], v[176:179], v[0:3], 0
	s_waitcnt vmcnt(26)
	v_mfma_f32_16x16x32_bf16 v[220:223], v[180:183], v[4:7], v[220:223]
	s_waitcnt vmcnt(25)
	v_mfma_f32_16x16x32_bf16 v[220:223], v[184:187], v[8:11], v[220:223]
	s_waitcnt vmcnt(24)
	v_mfma_f32_16x16x32_bf16 v[220:223], v[188:191], v[12:15], v[220:223]
	ds_write_b128 v249, v[212:215] offset:40960
	s_waitcnt vmcnt(23)
	v_mfma_f32_16x16x32_bf16 v[224:227], v[64:67], v[0:3], 0
	s_waitcnt vmcnt(22)
	v_mfma_f32_16x16x32_bf16 v[224:227], v[68:71], v[4:7], v[224:227]
	s_waitcnt vmcnt(21)
	v_mfma_f32_16x16x32_bf16 v[224:227], v[72:75], v[8:11], v[224:227]
	s_waitcnt vmcnt(20)
	v_mfma_f32_16x16x32_bf16 v[224:227], v[76:79], v[12:15], v[224:227]
	ds_write_b128 v249, v[216:219] offset:49152
	s_waitcnt vmcnt(19)
	v_mfma_f32_16x16x32_bf16 v[228:231], v[80:83], v[0:3], 0
	s_waitcnt vmcnt(18)
	v_mfma_f32_16x16x32_bf16 v[228:231], v[84:87], v[4:7], v[228:231]
	s_waitcnt vmcnt(17)
	v_mfma_f32_16x16x32_bf16 v[228:231], v[88:91], v[8:11], v[228:231]
	s_waitcnt vmcnt(16)
	v_mfma_f32_16x16x32_bf16 v[228:231], v[92:95], v[12:15], v[228:231]
	ds_write_b128 v249, v[220:223] offset:57344
	s_waitcnt vmcnt(15)
	v_mfma_f32_16x16x32_bf16 v[232:235], v[96:99], v[0:3], 0
	s_waitcnt vmcnt(14)
	v_mfma_f32_16x16x32_bf16 v[232:235], v[100:103], v[4:7], v[232:235]
	s_waitcnt vmcnt(13)
	v_mfma_f32_16x16x32_bf16 v[232:235], v[104:107], v[8:11], v[232:235]
	s_waitcnt vmcnt(12)
	v_mfma_f32_16x16x32_bf16 v[232:235], v[108:111], v[12:15], v[232:235]
	ds_write_b128 v62, v[224:227]
	s_waitcnt vmcnt(11)
	v_mfma_f32_16x16x32_bf16 v[236:239], v[112:115], v[0:3], 0
	s_waitcnt vmcnt(10)
	v_mfma_f32_16x16x32_bf16 v[236:239], v[116:119], v[4:7], v[236:239]
	s_waitcnt vmcnt(9)
	v_mfma_f32_16x16x32_bf16 v[236:239], v[120:123], v[8:11], v[236:239]
	s_waitcnt vmcnt(8)
	v_mfma_f32_16x16x32_bf16 v[236:239], v[124:127], v[12:15], v[236:239]
	ds_write_b128 v62, v[228:231] offset:8192
	s_waitcnt vmcnt(7)
	v_mfma_f32_16x16x32_bf16 v[240:243], v[128:131], v[0:3], 0
	s_waitcnt vmcnt(6)
	v_mfma_f32_16x16x32_bf16 v[240:243], v[132:135], v[4:7], v[240:243]
	s_waitcnt vmcnt(5)
	v_mfma_f32_16x16x32_bf16 v[240:243], v[136:139], v[8:11], v[240:243]
	s_waitcnt vmcnt(4)
	v_mfma_f32_16x16x32_bf16 v[240:243], v[140:143], v[12:15], v[240:243]
	ds_write_b128 v62, v[232:235] offset:16384
	s_waitcnt vmcnt(3)
	v_mfma_f32_16x16x32_bf16 v[244:247], v[144:147], v[0:3], 0
	s_waitcnt vmcnt(2)
	v_mfma_f32_16x16x32_bf16 v[244:247], v[148:151], v[4:7], v[244:247]
	s_waitcnt vmcnt(1)
	v_mfma_f32_16x16x32_bf16 v[244:247], v[152:155], v[8:11], v[244:247]
	s_waitcnt vmcnt(0)
	v_mfma_f32_16x16x32_bf16 v[244:247], v[156:159], v[12:15], v[244:247]
	ds_write_b128 v62, v[236:239] offset:24576
	s_andn2_b64 vcc, exec, s[4:5]
	s_nop 7
	ds_write_b128 v62, v[240:243] offset:32768
	ds_write_b128 v62, v[244:247] offset:40960
	s_waitcnt lgkmcnt(0)
	s_barrier
	s_cbranch_vccnz .LBB0_224
	s_ashr_i32 s23, s22, 11
	s_mul_hi_i32 s25, s23, 0x4800
	s_mulk_i32 s23, 0x4800
	s_add_u32 s24, s48, s23
	s_addc_u32 s25, s49, s25
	s_mul_i32 s23, s26, 0xffffe400
	s_mov_b32 s44, s15
	s_mov_b32 s45, s40
	s_branch .LBB0_229
